# phase 6 epilogue: accumulator 4x4 lane/register transposes (v_cndmask_b32_dpp) so x loads and out stores are 16-byte row-contiguous (16+16 per wave instead of 64+64 dword accesses)
# baseline (speedup 1.0000x reference)
.LBB0_370:
	v_or_b32_e32 v150, s10, v131
	v_add_lshl_u32 v151, v147, s11, 10
	v_add_lshl_u32 v148, v151, v150, 2
	v_and_b32_e32 v149, 3, v205
	v_mul_u32_u24_e32 v149, 0xffc, v149
	v_add_u32_e32 v148, v148, v149
	s_mov_b32 s11, s7
	s_mov_b32 s10, s6
	global_load_dwordx4 v[172:175], v148, s[36:37]
	global_load_dwordx4 v[176:179], v148, s[36:37] offset:128
	v_add_u32_e32 v149, 0x8000, v148
	global_load_dwordx4 v[180:183], v149, s[36:37]
	global_load_dwordx4 v[184:187], v149, s[36:37] offset:128
	v_add_u32_e32 v152, 0x10000, v148
	global_load_dwordx4 v[188:191], v152, s[36:37]
	global_load_dwordx4 v[192:195], v152, s[36:37] offset:128
	v_add_u32_e32 v153, 0x18000, v148
	global_load_dwordx4 v[196:199], v153, s[36:37]
	global_load_dwordx4 v[200:203], v153, s[36:37] offset:128
	s_mov_b32 vcc_lo, 0x55555555
	s_mov_b32 vcc_hi, 0x55555555
	v_cndmask_b32_dpp v208, v49, v48, vcc quad_perm:[1,0,3,2] row_mask:0xf bank_mask:0xf
	v_cndmask_b32_dpp v210, v51, v50, vcc quad_perm:[1,0,3,2] row_mask:0xf bank_mask:0xf
	v_cndmask_b32_dpp v212, v53, v52, vcc quad_perm:[1,0,3,2] row_mask:0xf bank_mask:0xf
	v_cndmask_b32_dpp v214, v55, v54, vcc quad_perm:[1,0,3,2] row_mask:0xf bank_mask:0xf
	v_cndmask_b32_dpp v216, v57, v56, vcc quad_perm:[1,0,3,2] row_mask:0xf bank_mask:0xf
	v_cndmask_b32_dpp v218, v59, v58, vcc quad_perm:[1,0,3,2] row_mask:0xf bank_mask:0xf
	v_cndmask_b32_dpp v220, v61, v60, vcc quad_perm:[1,0,3,2] row_mask:0xf bank_mask:0xf
	v_cndmask_b32_dpp v222, v63, v62, vcc quad_perm:[1,0,3,2] row_mask:0xf bank_mask:0xf
	s_mov_b32 vcc_lo, 0xaaaaaaaa
	s_mov_b32 vcc_hi, 0xaaaaaaaa
	v_cndmask_b32_dpp v209, v48, v49, vcc quad_perm:[1,0,3,2] row_mask:0xf bank_mask:0xf
	v_cndmask_b32_dpp v211, v50, v51, vcc quad_perm:[1,0,3,2] row_mask:0xf bank_mask:0xf
	v_cndmask_b32_dpp v213, v52, v53, vcc quad_perm:[1,0,3,2] row_mask:0xf bank_mask:0xf
	v_cndmask_b32_dpp v215, v54, v55, vcc quad_perm:[1,0,3,2] row_mask:0xf bank_mask:0xf
	v_cndmask_b32_dpp v217, v56, v57, vcc quad_perm:[1,0,3,2] row_mask:0xf bank_mask:0xf
	v_cndmask_b32_dpp v219, v58, v59, vcc quad_perm:[1,0,3,2] row_mask:0xf bank_mask:0xf
	v_cndmask_b32_dpp v221, v60, v61, vcc quad_perm:[1,0,3,2] row_mask:0xf bank_mask:0xf
	v_cndmask_b32_dpp v223, v62, v63, vcc quad_perm:[1,0,3,2] row_mask:0xf bank_mask:0xf
	s_mov_b32 vcc_lo, 0x33333333
	s_mov_b32 vcc_hi, 0x33333333
	v_cndmask_b32_dpp v48, v210, v208, vcc quad_perm:[2,3,0,1] row_mask:0xf bank_mask:0xf
	v_cndmask_b32_dpp v49, v211, v209, vcc quad_perm:[2,3,0,1] row_mask:0xf bank_mask:0xf
	v_cndmask_b32_dpp v52, v214, v212, vcc quad_perm:[2,3,0,1] row_mask:0xf bank_mask:0xf
	v_cndmask_b32_dpp v53, v215, v213, vcc quad_perm:[2,3,0,1] row_mask:0xf bank_mask:0xf
	v_cndmask_b32_dpp v56, v218, v216, vcc quad_perm:[2,3,0,1] row_mask:0xf bank_mask:0xf
	v_cndmask_b32_dpp v57, v219, v217, vcc quad_perm:[2,3,0,1] row_mask:0xf bank_mask:0xf
	v_cndmask_b32_dpp v60, v222, v220, vcc quad_perm:[2,3,0,1] row_mask:0xf bank_mask:0xf
	v_cndmask_b32_dpp v61, v223, v221, vcc quad_perm:[2,3,0,1] row_mask:0xf bank_mask:0xf
	s_mov_b32 vcc_lo, 0xcccccccc
	s_mov_b32 vcc_hi, 0xcccccccc
	v_cndmask_b32_dpp v50, v208, v210, vcc quad_perm:[2,3,0,1] row_mask:0xf bank_mask:0xf
	v_cndmask_b32_dpp v51, v209, v211, vcc quad_perm:[2,3,0,1] row_mask:0xf bank_mask:0xf
	v_cndmask_b32_dpp v54, v212, v214, vcc quad_perm:[2,3,0,1] row_mask:0xf bank_mask:0xf
	v_cndmask_b32_dpp v55, v213, v215, vcc quad_perm:[2,3,0,1] row_mask:0xf bank_mask:0xf
	v_cndmask_b32_dpp v58, v216, v218, vcc quad_perm:[2,3,0,1] row_mask:0xf bank_mask:0xf
	v_cndmask_b32_dpp v59, v217, v219, vcc quad_perm:[2,3,0,1] row_mask:0xf bank_mask:0xf
	v_cndmask_b32_dpp v62, v220, v222, vcc quad_perm:[2,3,0,1] row_mask:0xf bank_mask:0xf
	v_cndmask_b32_dpp v63, v221, v223, vcc quad_perm:[2,3,0,1] row_mask:0xf bank_mask:0xf
	s_mov_b32 vcc_lo, 0x55555555
	s_mov_b32 vcc_hi, 0x55555555
	v_cndmask_b32_dpp v208, v17, v16, vcc quad_perm:[1,0,3,2] row_mask:0xf bank_mask:0xf
	v_cndmask_b32_dpp v210, v19, v18, vcc quad_perm:[1,0,3,2] row_mask:0xf bank_mask:0xf
	v_cndmask_b32_dpp v212, v21, v20, vcc quad_perm:[1,0,3,2] row_mask:0xf bank_mask:0xf
	v_cndmask_b32_dpp v214, v23, v22, vcc quad_perm:[1,0,3,2] row_mask:0xf bank_mask:0xf
	v_cndmask_b32_dpp v216, v25, v24, vcc quad_perm:[1,0,3,2] row_mask:0xf bank_mask:0xf
	v_cndmask_b32_dpp v218, v27, v26, vcc quad_perm:[1,0,3,2] row_mask:0xf bank_mask:0xf
	v_cndmask_b32_dpp v220, v29, v28, vcc quad_perm:[1,0,3,2] row_mask:0xf bank_mask:0xf
	v_cndmask_b32_dpp v222, v31, v30, vcc quad_perm:[1,0,3,2] row_mask:0xf bank_mask:0xf
	s_mov_b32 vcc_lo, 0xaaaaaaaa
	s_mov_b32 vcc_hi, 0xaaaaaaaa
	v_cndmask_b32_dpp v209, v16, v17, vcc quad_perm:[1,0,3,2] row_mask:0xf bank_mask:0xf
	v_cndmask_b32_dpp v211, v18, v19, vcc quad_perm:[1,0,3,2] row_mask:0xf bank_mask:0xf
	v_cndmask_b32_dpp v213, v20, v21, vcc quad_perm:[1,0,3,2] row_mask:0xf bank_mask:0xf
	v_cndmask_b32_dpp v215, v22, v23, vcc quad_perm:[1,0,3,2] row_mask:0xf bank_mask:0xf
	v_cndmask_b32_dpp v217, v24, v25, vcc quad_perm:[1,0,3,2] row_mask:0xf bank_mask:0xf
	v_cndmask_b32_dpp v219, v26, v27, vcc quad_perm:[1,0,3,2] row_mask:0xf bank_mask:0xf
	v_cndmask_b32_dpp v221, v28, v29, vcc quad_perm:[1,0,3,2] row_mask:0xf bank_mask:0xf
	v_cndmask_b32_dpp v223, v30, v31, vcc quad_perm:[1,0,3,2] row_mask:0xf bank_mask:0xf
	s_mov_b32 vcc_lo, 0x33333333
	s_mov_b32 vcc_hi, 0x33333333
	v_cndmask_b32_dpp v16, v210, v208, vcc quad_perm:[2,3,0,1] row_mask:0xf bank_mask:0xf
	v_cndmask_b32_dpp v17, v211, v209, vcc quad_perm:[2,3,0,1] row_mask:0xf bank_mask:0xf
	v_cndmask_b32_dpp v20, v214, v212, vcc quad_perm:[2,3,0,1] row_mask:0xf bank_mask:0xf
	v_cndmask_b32_dpp v21, v215, v213, vcc quad_perm:[2,3,0,1] row_mask:0xf bank_mask:0xf
	v_cndmask_b32_dpp v24, v218, v216, vcc quad_perm:[2,3,0,1] row_mask:0xf bank_mask:0xf
	v_cndmask_b32_dpp v25, v219, v217, vcc quad_perm:[2,3,0,1] row_mask:0xf bank_mask:0xf
	v_cndmask_b32_dpp v28, v222, v220, vcc quad_perm:[2,3,0,1] row_mask:0xf bank_mask:0xf
	v_cndmask_b32_dpp v29, v223, v221, vcc quad_perm:[2,3,0,1] row_mask:0xf bank_mask:0xf
	s_mov_b32 vcc_lo, 0xcccccccc
	s_mov_b32 vcc_hi, 0xcccccccc
	v_cndmask_b32_dpp v18, v208, v210, vcc quad_perm:[2,3,0,1] row_mask:0xf bank_mask:0xf
	v_cndmask_b32_dpp v19, v209, v211, vcc quad_perm:[2,3,0,1] row_mask:0xf bank_mask:0xf
	v_cndmask_b32_dpp v22, v212, v214, vcc quad_perm:[2,3,0,1] row_mask:0xf bank_mask:0xf
	v_cndmask_b32_dpp v23, v213, v215, vcc quad_perm:[2,3,0,1] row_mask:0xf bank_mask:0xf
	v_cndmask_b32_dpp v26, v216, v218, vcc quad_perm:[2,3,0,1] row_mask:0xf bank_mask:0xf
	v_cndmask_b32_dpp v27, v217, v219, vcc quad_perm:[2,3,0,1] row_mask:0xf bank_mask:0xf
	v_cndmask_b32_dpp v30, v220, v222, vcc quad_perm:[2,3,0,1] row_mask:0xf bank_mask:0xf
	v_cndmask_b32_dpp v31, v221, v223, vcc quad_perm:[2,3,0,1] row_mask:0xf bank_mask:0xf
	s_mov_b32 vcc_lo, 0x55555555
	s_mov_b32 vcc_hi, 0x55555555
	v_cndmask_b32_dpp v208, v33, v32, vcc quad_perm:[1,0,3,2] row_mask:0xf bank_mask:0xf
	v_cndmask_b32_dpp v210, v35, v34, vcc quad_perm:[1,0,3,2] row_mask:0xf bank_mask:0xf
	v_cndmask_b32_dpp v212, v37, v36, vcc quad_perm:[1,0,3,2] row_mask:0xf bank_mask:0xf
	v_cndmask_b32_dpp v214, v39, v38, vcc quad_perm:[1,0,3,2] row_mask:0xf bank_mask:0xf
	v_cndmask_b32_dpp v216, v41, v40, vcc quad_perm:[1,0,3,2] row_mask:0xf bank_mask:0xf
	v_cndmask_b32_dpp v218, v43, v42, vcc quad_perm:[1,0,3,2] row_mask:0xf bank_mask:0xf
	v_cndmask_b32_dpp v220, v45, v44, vcc quad_perm:[1,0,3,2] row_mask:0xf bank_mask:0xf
	v_cndmask_b32_dpp v222, v47, v46, vcc quad_perm:[1,0,3,2] row_mask:0xf bank_mask:0xf
	s_mov_b32 vcc_lo, 0xaaaaaaaa
	s_mov_b32 vcc_hi, 0xaaaaaaaa
	v_cndmask_b32_dpp v209, v32, v33, vcc quad_perm:[1,0,3,2] row_mask:0xf bank_mask:0xf
	v_cndmask_b32_dpp v211, v34, v35, vcc quad_perm:[1,0,3,2] row_mask:0xf bank_mask:0xf
	v_cndmask_b32_dpp v213, v36, v37, vcc quad_perm:[1,0,3,2] row_mask:0xf bank_mask:0xf
	v_cndmask_b32_dpp v215, v38, v39, vcc quad_perm:[1,0,3,2] row_mask:0xf bank_mask:0xf
	v_cndmask_b32_dpp v217, v40, v41, vcc quad_perm:[1,0,3,2] row_mask:0xf bank_mask:0xf
	v_cndmask_b32_dpp v219, v42, v43, vcc quad_perm:[1,0,3,2] row_mask:0xf bank_mask:0xf
	v_cndmask_b32_dpp v221, v44, v45, vcc quad_perm:[1,0,3,2] row_mask:0xf bank_mask:0xf
	v_cndmask_b32_dpp v223, v46, v47, vcc quad_perm:[1,0,3,2] row_mask:0xf bank_mask:0xf
	s_mov_b32 vcc_lo, 0x33333333
	s_mov_b32 vcc_hi, 0x33333333
	v_cndmask_b32_dpp v32, v210, v208, vcc quad_perm:[2,3,0,1] row_mask:0xf bank_mask:0xf
	v_cndmask_b32_dpp v33, v211, v209, vcc quad_perm:[2,3,0,1] row_mask:0xf bank_mask:0xf
	v_cndmask_b32_dpp v36, v214, v212, vcc quad_perm:[2,3,0,1] row_mask:0xf bank_mask:0xf
	v_cndmask_b32_dpp v37, v215, v213, vcc quad_perm:[2,3,0,1] row_mask:0xf bank_mask:0xf
	v_cndmask_b32_dpp v40, v218, v216, vcc quad_perm:[2,3,0,1] row_mask:0xf bank_mask:0xf
	v_cndmask_b32_dpp v41, v219, v217, vcc quad_perm:[2,3,0,1] row_mask:0xf bank_mask:0xf
	v_cndmask_b32_dpp v44, v222, v220, vcc quad_perm:[2,3,0,1] row_mask:0xf bank_mask:0xf
	v_cndmask_b32_dpp v45, v223, v221, vcc quad_perm:[2,3,0,1] row_mask:0xf bank_mask:0xf
	s_mov_b32 vcc_lo, 0xcccccccc
	s_mov_b32 vcc_hi, 0xcccccccc
	v_cndmask_b32_dpp v34, v208, v210, vcc quad_perm:[2,3,0,1] row_mask:0xf bank_mask:0xf
	v_cndmask_b32_dpp v35, v209, v211, vcc quad_perm:[2,3,0,1] row_mask:0xf bank_mask:0xf
	v_cndmask_b32_dpp v38, v212, v214, vcc quad_perm:[2,3,0,1] row_mask:0xf bank_mask:0xf
	v_cndmask_b32_dpp v39, v213, v215, vcc quad_perm:[2,3,0,1] row_mask:0xf bank_mask:0xf
	v_cndmask_b32_dpp v42, v216, v218, vcc quad_perm:[2,3,0,1] row_mask:0xf bank_mask:0xf
	v_cndmask_b32_dpp v43, v217, v219, vcc quad_perm:[2,3,0,1] row_mask:0xf bank_mask:0xf
	v_cndmask_b32_dpp v46, v220, v222, vcc quad_perm:[2,3,0,1] row_mask:0xf bank_mask:0xf
	v_cndmask_b32_dpp v47, v221, v223, vcc quad_perm:[2,3,0,1] row_mask:0xf bank_mask:0xf
	s_mov_b32 vcc_lo, 0x55555555
	s_mov_b32 vcc_hi, 0x55555555
	v_cndmask_b32_dpp v208, v1, v0, vcc quad_perm:[1,0,3,2] row_mask:0xf bank_mask:0xf
	v_cndmask_b32_dpp v210, v3, v2, vcc quad_perm:[1,0,3,2] row_mask:0xf bank_mask:0xf
	v_cndmask_b32_dpp v212, v5, v4, vcc quad_perm:[1,0,3,2] row_mask:0xf bank_mask:0xf
	v_cndmask_b32_dpp v214, v7, v6, vcc quad_perm:[1,0,3,2] row_mask:0xf bank_mask:0xf
	v_cndmask_b32_dpp v216, v9, v8, vcc quad_perm:[1,0,3,2] row_mask:0xf bank_mask:0xf
	v_cndmask_b32_dpp v218, v11, v10, vcc quad_perm:[1,0,3,2] row_mask:0xf bank_mask:0xf
	v_cndmask_b32_dpp v220, v13, v12, vcc quad_perm:[1,0,3,2] row_mask:0xf bank_mask:0xf
	v_cndmask_b32_dpp v222, v15, v14, vcc quad_perm:[1,0,3,2] row_mask:0xf bank_mask:0xf
	s_mov_b32 vcc_lo, 0xaaaaaaaa
	s_mov_b32 vcc_hi, 0xaaaaaaaa
	v_cndmask_b32_dpp v209, v0, v1, vcc quad_perm:[1,0,3,2] row_mask:0xf bank_mask:0xf
	v_cndmask_b32_dpp v211, v2, v3, vcc quad_perm:[1,0,3,2] row_mask:0xf bank_mask:0xf
	v_cndmask_b32_dpp v213, v4, v5, vcc quad_perm:[1,0,3,2] row_mask:0xf bank_mask:0xf
	v_cndmask_b32_dpp v215, v6, v7, vcc quad_perm:[1,0,3,2] row_mask:0xf bank_mask:0xf
	v_cndmask_b32_dpp v217, v8, v9, vcc quad_perm:[1,0,3,2] row_mask:0xf bank_mask:0xf
	v_cndmask_b32_dpp v219, v10, v11, vcc quad_perm:[1,0,3,2] row_mask:0xf bank_mask:0xf
	v_cndmask_b32_dpp v221, v12, v13, vcc quad_perm:[1,0,3,2] row_mask:0xf bank_mask:0xf
	v_cndmask_b32_dpp v223, v14, v15, vcc quad_perm:[1,0,3,2] row_mask:0xf bank_mask:0xf
	s_mov_b32 vcc_lo, 0x33333333
	s_mov_b32 vcc_hi, 0x33333333
	v_cndmask_b32_dpp v0, v210, v208, vcc quad_perm:[2,3,0,1] row_mask:0xf bank_mask:0xf
	v_cndmask_b32_dpp v1, v211, v209, vcc quad_perm:[2,3,0,1] row_mask:0xf bank_mask:0xf
	v_cndmask_b32_dpp v4, v214, v212, vcc quad_perm:[2,3,0,1] row_mask:0xf bank_mask:0xf
	v_cndmask_b32_dpp v5, v215, v213, vcc quad_perm:[2,3,0,1] row_mask:0xf bank_mask:0xf
	v_cndmask_b32_dpp v8, v218, v216, vcc quad_perm:[2,3,0,1] row_mask:0xf bank_mask:0xf
	v_cndmask_b32_dpp v9, v219, v217, vcc quad_perm:[2,3,0,1] row_mask:0xf bank_mask:0xf
	v_cndmask_b32_dpp v12, v222, v220, vcc quad_perm:[2,3,0,1] row_mask:0xf bank_mask:0xf
	v_cndmask_b32_dpp v13, v223, v221, vcc quad_perm:[2,3,0,1] row_mask:0xf bank_mask:0xf
	s_mov_b32 vcc_lo, 0xcccccccc
	s_mov_b32 vcc_hi, 0xcccccccc
	v_cndmask_b32_dpp v2, v208, v210, vcc quad_perm:[2,3,0,1] row_mask:0xf bank_mask:0xf
	v_cndmask_b32_dpp v3, v209, v211, vcc quad_perm:[2,3,0,1] row_mask:0xf bank_mask:0xf
	v_cndmask_b32_dpp v6, v212, v214, vcc quad_perm:[2,3,0,1] row_mask:0xf bank_mask:0xf
	v_cndmask_b32_dpp v7, v213, v215, vcc quad_perm:[2,3,0,1] row_mask:0xf bank_mask:0xf
	v_cndmask_b32_dpp v10, v216, v218, vcc quad_perm:[2,3,0,1] row_mask:0xf bank_mask:0xf
	v_cndmask_b32_dpp v11, v217, v219, vcc quad_perm:[2,3,0,1] row_mask:0xf bank_mask:0xf
	v_cndmask_b32_dpp v14, v220, v222, vcc quad_perm:[2,3,0,1] row_mask:0xf bank_mask:0xf
	v_cndmask_b32_dpp v15, v221, v223, vcc quad_perm:[2,3,0,1] row_mask:0xf bank_mask:0xf
	s_waitcnt vmcnt(7)
	v_pk_add_f32 v[172:173], v[48:49], v[172:173]
	v_pk_add_f32 v[174:175], v[50:51], v[174:175]
	global_store_dwordx4 v148, v[172:175], s[24:25]
	v_add_u32_e32 v154, 0x20000, v148
	global_load_dwordx4 v[208:211], v154, s[36:37]
	s_waitcnt vmcnt(8)
	v_pk_add_f32 v[176:177], v[16:17], v[176:177]
	v_pk_add_f32 v[178:179], v[18:19], v[178:179]
	global_store_dwordx4 v148, v[176:179], s[24:25] offset:128
	v_add_u32_e32 v150, 0x20000, v148
	global_load_dwordx4 v[212:215], v150, s[36:37] offset:128
	s_waitcnt vmcnt(9)
	v_pk_add_f32 v[180:181], v[52:53], v[180:181]
	v_pk_add_f32 v[182:183], v[54:55], v[182:183]
	v_add_u32_e32 v151, 0x8000, v148
	global_store_dwordx4 v151, v[180:183], s[24:25]
	v_add_u32_e32 v149, 0x28000, v148
	global_load_dwordx4 v[216:219], v149, s[36:37]
	s_waitcnt vmcnt(10)
	v_pk_add_f32 v[184:185], v[20:21], v[184:185]
	v_pk_add_f32 v[186:187], v[22:23], v[186:187]
	v_add_u32_e32 v152, 0x8000, v148
	global_store_dwordx4 v152, v[184:187], s[24:25] offset:128
	v_add_u32_e32 v153, 0x28000, v148
	global_load_dwordx4 v[220:223], v153, s[36:37] offset:128
	s_waitcnt vmcnt(11)
	v_pk_add_f32 v[188:189], v[56:57], v[188:189]
	v_pk_add_f32 v[190:191], v[58:59], v[190:191]
	v_add_u32_e32 v154, 0x10000, v148
	global_store_dwordx4 v154, v[188:191], s[24:25]
	v_add_u32_e32 v150, 0x30000, v148
	global_load_dwordx4 v[224:227], v150, s[36:37]
	s_waitcnt vmcnt(12)
	v_pk_add_f32 v[192:193], v[24:25], v[192:193]
	v_pk_add_f32 v[194:195], v[26:27], v[194:195]
	v_add_u32_e32 v151, 0x10000, v148
	global_store_dwordx4 v151, v[192:195], s[24:25] offset:128
	v_add_u32_e32 v149, 0x30000, v148
	global_load_dwordx4 v[228:231], v149, s[36:37] offset:128
	s_waitcnt vmcnt(13)
	v_pk_add_f32 v[196:197], v[60:61], v[196:197]
	v_pk_add_f32 v[198:199], v[62:63], v[198:199]
	v_add_u32_e32 v152, 0x18000, v148
	global_store_dwordx4 v152, v[196:199], s[24:25]
	v_add_u32_e32 v153, 0x38000, v148
	global_load_dwordx4 v[232:235], v153, s[36:37]
	s_waitcnt vmcnt(14)
	v_pk_add_f32 v[200:201], v[28:29], v[200:201]
	v_pk_add_f32 v[202:203], v[30:31], v[202:203]
	v_add_u32_e32 v154, 0x18000, v148
	global_store_dwordx4 v154, v[200:203], s[24:25] offset:128
	v_add_u32_e32 v150, 0x38000, v148
	global_load_dwordx4 v[172:175], v150, s[36:37] offset:128
	s_waitcnt vmcnt(14)
	v_pk_add_f32 v[208:209], v[32:33], v[208:209]
	v_pk_add_f32 v[210:211], v[34:35], v[210:211]
	v_add_u32_e32 v151, 0x20000, v148
	global_store_dwordx4 v151, v[208:211], s[24:25]
	s_waitcnt vmcnt(13)
	v_pk_add_f32 v[212:213], v[0:1], v[212:213]
	v_pk_add_f32 v[214:215], v[2:3], v[214:215]
	v_add_u32_e32 v149, 0x20000, v148
	global_store_dwordx4 v149, v[212:215], s[24:25] offset:128
	s_waitcnt vmcnt(12)
	v_pk_add_f32 v[216:217], v[36:37], v[216:217]
	v_pk_add_f32 v[218:219], v[38:39], v[218:219]
	v_add_u32_e32 v152, 0x28000, v148
	global_store_dwordx4 v152, v[216:219], s[24:25]
	s_waitcnt vmcnt(11)
	v_pk_add_f32 v[220:221], v[4:5], v[220:221]
	v_pk_add_f32 v[222:223], v[6:7], v[222:223]
	v_add_u32_e32 v153, 0x28000, v148
	global_store_dwordx4 v153, v[220:223], s[24:25] offset:128
	s_waitcnt vmcnt(10)
	v_pk_add_f32 v[224:225], v[40:41], v[224:225]
	v_pk_add_f32 v[226:227], v[42:43], v[226:227]
	v_add_u32_e32 v154, 0x30000, v148
	global_store_dwordx4 v154, v[224:227], s[24:25]
	s_waitcnt vmcnt(9)
	v_pk_add_f32 v[228:229], v[8:9], v[228:229]
	v_pk_add_f32 v[230:231], v[10:11], v[230:231]
	v_add_u32_e32 v150, 0x30000, v148
	global_store_dwordx4 v150, v[228:231], s[24:25] offset:128
	s_waitcnt vmcnt(8)
	v_pk_add_f32 v[232:233], v[44:45], v[232:233]
	v_pk_add_f32 v[234:235], v[46:47], v[234:235]
	v_add_u32_e32 v151, 0x38000, v148
	global_store_dwordx4 v151, v[232:235], s[24:25]
	s_waitcnt vmcnt(7)
	v_pk_add_f32 v[172:173], v[12:13], v[172:173]
	v_pk_add_f32 v[174:175], v[14:15], v[174:175]
	v_add_u32_e32 v149, 0x38000, v148
	global_store_dwordx4 v149, v[172:175], s[24:25] offset:128
	s_andn2_b64 vcc, exec, s[4:5]
	s_cbranch_vccz .LBB0_381
